# v8
# speedup vs baseline: 1.0013x; 1.0013x over previous
.LBB0_105:
	s_andn2_b64 vcc, exec, s[4:5]
	s_cbranch_vccnz .LBB0_148
	v_and_b32_e32 v6, 15, v1
	v_bfe_u32 v8, v1, 4, 2
	v_lshlrev_b32_e32 v9, 2, v1
	v_ashrrev_i32_e32 v10, 8, v1
	v_lshlrev_b32_e32 v4, 4, v8
	v_lshlrev_b32_e32 v7, 6, v6
	v_and_b32_e32 v12, 32, v9
	v_bfe_u32 v5, v1, 6, 2
	v_bitop3_b32 v13, v4, v12, v7 bitop3:0x36
	v_lshlrev_b32_e32 v7, 6, v10
	v_ashrrev_i32_e32 v129, 31, v7
	v_or_b32_e32 v128, v7, v6
	v_lshlrev_b32_e32 v6, 6, v5
	v_mov_b32_e32 v7, v185
	v_readlane_b32 s10, v247, 13
	v_lshlrev_b32_e32 v11, 12, v5
	v_lshl_add_u64 v[6:7], s[56:57], 0, v[6:7]
	v_lshlrev_b32_e32 v8, 3, v8
	v_mov_b32_e32 v9, v185
	v_cmp_eq_u32_e64 s[8:9], 0, v5
	v_mov_b32_e32 v5, v185
	v_readlane_b32 s11, v247, 14
	s_movk_i32 s1, 0x100
	v_lshl_add_u64 v[130:131], v[6:7], 0, v[8:9]
	v_lshl_add_u64 v[132:133], s[10:11], 0, v[4:5]
	v_readlane_b32 s10, v247, 11
	v_lshlrev_b32_e32 v9, 15, v0
	v_cmp_gt_u32_e64 s[6:7], s1, v1
	v_readlane_b32 s11, v247, 12
	v_lshlrev_b32_e32 v1, 6, v1
	s_movk_i32 s1, 0x3c0
	v_and_b32_e32 v9, 0xffff0000, v9
	v_lshl_add_u64 v[134:135], s[10:11], 0, v[4:5]
	v_lshlrev_b32_e32 v5, 13, v10
	v_and_or_b32 v1, v1, s1, v4
	v_lshl_add_u32 v2, v2, 12, v9
	v_and_b32_e32 v0, 1, v0
	v_add_u32_e32 v14, s72, v13
	v_add_u32_e32 v15, s93, v13
	v_add_u32_e32 v16, s86, v13
	v_add_u32_e32 v17, s83, v13
	v_add_u32_e32 v6, 0, v13
	v_xad_u32 v1, v1, v12, 0
	v_or_b32_e32 v4, 0x800, v5
	v_or_b32_e32 v7, 0x1000, v5
	v_or_b32_e32 v8, 0x1800, v5
	v_lshl_or_b32 v0, v0, 6, v2
	v_cmp_eq_u32_e64 s[4:5], 1, v10
	v_lshl_add_u32 v136, v3, 1, v0
	v_mov_b32_e32 v137, v185
	v_add_u32_e32 v158, v14, v11
	v_add_u32_e32 v159, v6, v5
	v_add_u32_e32 v160, v1, v4
	v_add_u32_e32 v161, v1, v7
	v_add_u32_e32 v162, v1, v8
	v_add_u32_e32 v163, v15, v11
	v_add_u32_e32 v164, v16, v11
	v_add_u32_e32 v165, v17, v11
	s_branch .LBB0_108
.LBB0_108:
	s_waitcnt vmcnt(0)
.Lseam_qkvrot:
	s_and_saveexec_b64 s[10:11], s[4:5]
	s_cbranch_execz .LBB0_110
	s_barrier

.LBB0_116:
	s_lshr_b32 s3, s3, 19
	s_add_i32 s13, s2, s3
	s_and_b32 s3, s13, 0xffffe000
	s_sub_i32 s16, s2, s3
	s_cmpk_lt_i32 s0, 0x1000
	v_add_u32_e32 v166, s16, v128
	s_cselect_b64 s[2:3], -1, 0
	v_lshlrev_b32_e32 v142, 4, v166
	s_and_b64 s[2:3], s[8:9], s[2:3]
	v_ashrrev_i32_e32 v143, 31, v142
	s_lshr_b32 s1, s1, 21
	s_add_i32 s1, s0, s1
	s_ashr_i32 s18, s1, 11
	s_and_b32 s1, s1, 0xf800
	s_sub_i32 s0, s0, s1
	s_sext_i32_i16 s1, s0
	s_bfe_u32 s1, s1, 0x70018
	s_add_i32 s0, s0, s1
	s_ashr_i32 s13, s13, 13
	s_sext_i32_i16 s0, s0
	s_ashr_i32 s0, s0, 7
	s_lshl_b32 s1, s13, 4
	s_ashr_i32 s19, s18, 31
	s_add_i32 s0, s1, s0
	s_lshl_b64 s[18:19], s[18:19], 27
	s_ashr_i32 s17, s16, 31
	s_ashr_i32 s1, s0, 31
	v_lshl_add_u64 v[138:139], v[128:129], 0, s[16:17]
	v_lshl_add_u64 v[144:145], v[130:131], 0, s[18:19]
	s_lshl_b64 s[16:17], s[0:1], 21
	v_lshlrev_b64 v[138:139], 8, v[138:139]
	v_lshl_add_u64 v[140:141], v[144:145], 0, s[16:17]
	v_lshl_add_u64 v[146:147], v[140:141], 0, v[138:139]
	s_and_saveexec_b64 s[18:19], s[2:3]
	s_cbranch_execz .Lrot_skip
	v_lshlrev_b64 v[142:143], 2, v[142:143]
	s_mov_b64 s[16:17], 0x2000
	v_lshl_add_u64 v[138:139], v[134:135], 0, v[142:143]
	v_lshl_add_u64 v[140:141], v[132:133], 0, v[142:143]
	v_lshl_add_u64 v[144:145], v[138:139], 0, s[16:17]
	v_lshl_add_u64 v[166:167], v[140:141], 0, s[16:17]
	global_load_dwordx4 v[206:209], v[138:139], off
	global_load_dwordx4 v[210:213], v[140:141], off
	global_load_dwordx4 v[214:217], v[138:139], off offset:1024
	global_load_dwordx4 v[218:221], v[140:141], off offset:1024
	global_load_dwordx4 v[222:225], v[138:139], off offset:2048
	global_load_dwordx4 v[226:229], v[140:141], off offset:2048
	global_load_dwordx4 v[230:233], v[138:139], off offset:3072
	global_load_dwordx4 v[234:237], v[140:141], off offset:3072
	global_load_dwordx4 v[190:193], v[144:145], off
	global_load_dwordx4 v[194:197], v[166:167], off
	global_load_dwordx4 v[238:241], v[144:145], off offset:1024
	global_load_dwordx4 v[242:245], v[166:167], off offset:1024
	s_waitcnt vmcnt(10)
	v_pk_mul_f32 v[168:169], v[122:123], v[208:209]
	v_pk_mul_f32 v[170:171], v[120:121], v[206:207]
	v_pk_mul_f32 v[174:175], v[126:127], v[208:209]
	v_pk_mul_f32 v[172:173], v[124:125], v[206:207]
	v_pk_fma_f32 v[126:127], v[126:127], v[212:213], v[168:169] neg_lo:[0,0,1] neg_hi:[0,0,1]
	v_pk_fma_f32 v[124:125], v[124:125], v[210:211], v[170:171] neg_lo:[0,0,1] neg_hi:[0,0,1]
	v_pk_fma_f32 v[122:123], v[122:123], v[212:213], v[174:175]
	v_pk_fma_f32 v[120:121], v[120:121], v[210:211], v[172:173]
	v_pk_mul_f32 v[168:169], v[90:91], v[208:209]
	v_pk_mul_f32 v[170:171], v[88:89], v[206:207]
	v_pk_mul_f32 v[174:175], v[94:95], v[208:209]
	v_pk_mul_f32 v[172:173], v[92:93], v[206:207]
	v_pk_fma_f32 v[94:95], v[94:95], v[212:213], v[168:169] neg_lo:[0,0,1] neg_hi:[0,0,1]
	v_pk_fma_f32 v[92:93], v[92:93], v[210:211], v[170:171] neg_lo:[0,0,1] neg_hi:[0,0,1]
	v_pk_fma_f32 v[90:91], v[90:91], v[212:213], v[174:175]
	v_pk_fma_f32 v[88:89], v[88:89], v[210:211], v[172:173]
	s_waitcnt vmcnt(8)
	v_pk_mul_f32 v[168:169], v[114:115], v[216:217]
	v_pk_mul_f32 v[170:171], v[112:113], v[214:215]
	v_pk_mul_f32 v[174:175], v[118:119], v[216:217]
	v_pk_mul_f32 v[172:173], v[116:117], v[214:215]
	v_pk_fma_f32 v[118:119], v[118:119], v[220:221], v[168:169] neg_lo:[0,0,1] neg_hi:[0,0,1]
	v_pk_fma_f32 v[116:117], v[116:117], v[218:219], v[170:171] neg_lo:[0,0,1] neg_hi:[0,0,1]
	v_pk_fma_f32 v[114:115], v[114:115], v[220:221], v[174:175]
	v_pk_fma_f32 v[112:113], v[112:113], v[218:219], v[172:173]
	v_pk_mul_f32 v[168:169], v[82:83], v[216:217]
	v_pk_mul_f32 v[170:171], v[80:81], v[214:215]
	v_pk_mul_f32 v[174:175], v[86:87], v[216:217]
	v_pk_mul_f32 v[172:173], v[84:85], v[214:215]
	v_pk_fma_f32 v[86:87], v[86:87], v[220:221], v[168:169] neg_lo:[0,0,1] neg_hi:[0,0,1]
	v_pk_fma_f32 v[84:85], v[84:85], v[218:219], v[170:171] neg_lo:[0,0,1] neg_hi:[0,0,1]
	v_pk_fma_f32 v[82:83], v[82:83], v[220:221], v[174:175]
	v_pk_fma_f32 v[80:81], v[80:81], v[218:219], v[172:173]
	global_load_dwordx4 v[206:209], v[144:145], off offset:2048
	global_load_dwordx4 v[210:213], v[166:167], off offset:2048
	global_load_dwordx4 v[214:217], v[144:145], off offset:3072
	global_load_dwordx4 v[218:221], v[166:167], off offset:3072
	s_waitcnt vmcnt(10)
	v_pk_mul_f32 v[168:169], v[106:107], v[224:225]
	v_pk_mul_f32 v[170:171], v[104:105], v[222:223]
	v_pk_mul_f32 v[174:175], v[110:111], v[224:225]
	v_pk_mul_f32 v[172:173], v[108:109], v[222:223]
	v_pk_fma_f32 v[110:111], v[110:111], v[228:229], v[168:169] neg_lo:[0,0,1] neg_hi:[0,0,1]
	v_pk_fma_f32 v[108:109], v[108:109], v[226:227], v[170:171] neg_lo:[0,0,1] neg_hi:[0,0,1]
	v_pk_fma_f32 v[106:107], v[106:107], v[228:229], v[174:175]
	v_pk_fma_f32 v[104:105], v[104:105], v[226:227], v[172:173]
	v_pk_mul_f32 v[168:169], v[74:75], v[224:225]
	v_pk_mul_f32 v[170:171], v[72:73], v[222:223]
	v_pk_mul_f32 v[174:175], v[78:79], v[224:225]
	v_pk_mul_f32 v[172:173], v[76:77], v[222:223]
	v_pk_fma_f32 v[78:79], v[78:79], v[228:229], v[168:169] neg_lo:[0,0,1] neg_hi:[0,0,1]
	v_pk_fma_f32 v[76:77], v[76:77], v[226:227], v[170:171] neg_lo:[0,0,1] neg_hi:[0,0,1]
	v_pk_fma_f32 v[74:75], v[74:75], v[228:229], v[174:175]
	v_pk_fma_f32 v[72:73], v[72:73], v[226:227], v[172:173]
	s_waitcnt vmcnt(8)
	v_pk_mul_f32 v[168:169], v[98:99], v[232:233]
	v_pk_mul_f32 v[170:171], v[96:97], v[230:231]
	v_pk_mul_f32 v[174:175], v[102:103], v[232:233]
	v_pk_mul_f32 v[172:173], v[100:101], v[230:231]
	v_pk_fma_f32 v[102:103], v[102:103], v[236:237], v[168:169] neg_lo:[0,0,1] neg_hi:[0,0,1]
	v_pk_fma_f32 v[100:101], v[100:101], v[234:235], v[170:171] neg_lo:[0,0,1] neg_hi:[0,0,1]
	v_pk_fma_f32 v[98:99], v[98:99], v[236:237], v[174:175]
	v_pk_fma_f32 v[96:97], v[96:97], v[234:235], v[172:173]
	v_pk_mul_f32 v[168:169], v[66:67], v[232:233]
	v_pk_mul_f32 v[170:171], v[64:65], v[230:231]
	v_pk_mul_f32 v[174:175], v[70:71], v[232:233]
	v_pk_mul_f32 v[172:173], v[68:69], v[230:231]
	v_pk_fma_f32 v[70:71], v[70:71], v[236:237], v[168:169] neg_lo:[0,0,1] neg_hi:[0,0,1]
	v_pk_fma_f32 v[68:69], v[68:69], v[234:235], v[170:171] neg_lo:[0,0,1] neg_hi:[0,0,1]
	v_pk_fma_f32 v[66:67], v[66:67], v[236:237], v[174:175]
	v_pk_fma_f32 v[64:65], v[64:65], v[234:235], v[172:173]
	s_waitcnt vmcnt(6)
	v_pk_mul_f32 v[168:169], v[58:59], v[192:193]
	v_pk_mul_f32 v[170:171], v[56:57], v[190:191]
	v_pk_mul_f32 v[174:175], v[62:63], v[192:193]
	v_pk_mul_f32 v[172:173], v[60:61], v[190:191]
	v_pk_fma_f32 v[62:63], v[62:63], v[196:197], v[168:169] neg_lo:[0,0,1] neg_hi:[0,0,1]
	v_pk_fma_f32 v[60:61], v[60:61], v[194:195], v[170:171] neg_lo:[0,0,1] neg_hi:[0,0,1]
	v_pk_fma_f32 v[58:59], v[58:59], v[196:197], v[174:175]
	v_pk_fma_f32 v[56:57], v[56:57], v[194:195], v[172:173]
	v_pk_mul_f32 v[168:169], v[26:27], v[192:193]
	v_pk_mul_f32 v[170:171], v[24:25], v[190:191]
	v_pk_mul_f32 v[174:175], v[30:31], v[192:193]
	v_pk_mul_f32 v[172:173], v[28:29], v[190:191]
	v_pk_fma_f32 v[30:31], v[30:31], v[196:197], v[168:169] neg_lo:[0,0,1] neg_hi:[0,0,1]
	v_pk_fma_f32 v[28:29], v[28:29], v[194:195], v[170:171] neg_lo:[0,0,1] neg_hi:[0,0,1]
	v_pk_fma_f32 v[26:27], v[26:27], v[196:197], v[174:175]
	v_pk_fma_f32 v[24:25], v[24:25], v[194:195], v[172:173]
	s_waitcnt vmcnt(4)
	v_pk_mul_f32 v[168:169], v[50:51], v[240:241]
	v_pk_mul_f32 v[170:171], v[48:49], v[238:239]
	v_pk_mul_f32 v[174:175], v[54:55], v[240:241]
	v_pk_mul_f32 v[172:173], v[52:53], v[238:239]
	v_pk_fma_f32 v[54:55], v[54:55], v[244:245], v[168:169] neg_lo:[0,0,1] neg_hi:[0,0,1]
	v_pk_fma_f32 v[52:53], v[52:53], v[242:243], v[170:171] neg_lo:[0,0,1] neg_hi:[0,0,1]
	v_pk_fma_f32 v[50:51], v[50:51], v[244:245], v[174:175]
	v_pk_fma_f32 v[48:49], v[48:49], v[242:243], v[172:173]
	v_pk_mul_f32 v[168:169], v[18:19], v[240:241]
	v_pk_mul_f32 v[170:171], v[16:17], v[238:239]
	v_pk_mul_f32 v[174:175], v[22:23], v[240:241]
	v_pk_mul_f32 v[172:173], v[20:21], v[238:239]
	v_pk_fma_f32 v[22:23], v[22:23], v[244:245], v[168:169] neg_lo:[0,0,1] neg_hi:[0,0,1]
	v_pk_fma_f32 v[20:21], v[20:21], v[242:243], v[170:171] neg_lo:[0,0,1] neg_hi:[0,0,1]
	v_pk_fma_f32 v[18:19], v[18:19], v[244:245], v[174:175]
	v_pk_fma_f32 v[16:17], v[16:17], v[242:243], v[172:173]
	s_waitcnt vmcnt(2)
	v_pk_mul_f32 v[168:169], v[42:43], v[208:209]
	v_pk_mul_f32 v[170:171], v[40:41], v[206:207]
	v_pk_mul_f32 v[174:175], v[46:47], v[208:209]
	v_pk_mul_f32 v[172:173], v[44:45], v[206:207]
	v_pk_fma_f32 v[46:47], v[46:47], v[212:213], v[168:169] neg_lo:[0,0,1] neg_hi:[0,0,1]
	v_pk_fma_f32 v[44:45], v[44:45], v[210:211], v[170:171] neg_lo:[0,0,1] neg_hi:[0,0,1]
	v_pk_fma_f32 v[42:43], v[42:43], v[212:213], v[174:175]
	v_pk_fma_f32 v[40:41], v[40:41], v[210:211], v[172:173]
	v_pk_mul_f32 v[168:169], v[10:11], v[208:209]
	v_pk_mul_f32 v[170:171], v[8:9], v[206:207]
	v_pk_mul_f32 v[174:175], v[14:15], v[208:209]
	v_pk_mul_f32 v[172:173], v[12:13], v[206:207]
	v_pk_fma_f32 v[14:15], v[14:15], v[212:213], v[168:169] neg_lo:[0,0,1] neg_hi:[0,0,1]
	v_pk_fma_f32 v[12:13], v[12:13], v[210:211], v[170:171] neg_lo:[0,0,1] neg_hi:[0,0,1]
	v_pk_fma_f32 v[10:11], v[10:11], v[212:213], v[174:175]
	v_pk_fma_f32 v[8:9], v[8:9], v[210:211], v[172:173]
	s_waitcnt vmcnt(0)
	v_pk_mul_f32 v[168:169], v[34:35], v[216:217]
	v_pk_mul_f32 v[170:171], v[32:33], v[214:215]
	v_pk_mul_f32 v[174:175], v[38:39], v[216:217]
	v_pk_mul_f32 v[172:173], v[36:37], v[214:215]
	v_pk_fma_f32 v[38:39], v[38:39], v[220:221], v[168:169] neg_lo:[0,0,1] neg_hi:[0,0,1]
	v_pk_fma_f32 v[36:37], v[36:37], v[218:219], v[170:171] neg_lo:[0,0,1] neg_hi:[0,0,1]
	v_pk_fma_f32 v[34:35], v[34:35], v[220:221], v[174:175]
	v_pk_fma_f32 v[32:33], v[32:33], v[218:219], v[172:173]
	v_pk_mul_f32 v[168:169], v[2:3], v[216:217]
	v_pk_mul_f32 v[170:171], v[0:1], v[214:215]
	v_pk_mul_f32 v[174:175], v[6:7], v[216:217]
	v_pk_mul_f32 v[172:173], v[4:5], v[214:215]
	v_pk_fma_f32 v[6:7], v[6:7], v[220:221], v[168:169] neg_lo:[0,0,1] neg_hi:[0,0,1]
	v_pk_fma_f32 v[4:5], v[4:5], v[218:219], v[170:171] neg_lo:[0,0,1] neg_hi:[0,0,1]
	v_pk_fma_f32 v[2:3], v[2:3], v[220:221], v[174:175]
	v_pk_fma_f32 v[0:1], v[0:1], v[218:219], v[172:173]
.Lrot_skip:
	s_or_b64 exec, exec, s[18:19]
	v_bfe_u32 v142, v187, 4, 1
	v_mov_b32_e32 v143, 0
	v_mul_u32_u24_e32 v142, 24, v142
	s_mov_b64 s[16:17], 0x1000
	s_mov_b64 s[18:19], 0x2000
	v_lshl_add_u64 v[146:147], v[146:147], 0, v[142:143]
	v_lshl_add_u64 v[168:169], v[146:147], 0, s[16:17]
	v_lshl_add_u64 v[170:171], v[168:169], 0, s[18:19]
	s_mov_b64 s[18:19], 0x200000
	v_lshl_add_u64 v[172:173], v[168:169], 0, s[18:19]
	v_lshl_add_u64 v[174:175], v[170:171], 0, s[18:19]
	s_mov_b64 s[18:19], 0x8000
	v_lshl_add_u64 v[176:177], v[168:169], 0, s[18:19]
	v_lshl_add_u64 v[178:179], v[170:171], 0, s[18:19]
	v_lshl_add_u64 v[180:181], v[172:173], 0, s[18:19]
	v_lshl_add_u64 v[182:183], v[174:175], 0, s[18:19]
	v_cvt_pk_bf16_f32 v124, v124, v125
	v_cvt_pk_bf16_f32 v125, v126, v127
	v_cvt_pk_bf16_f32 v126, v120, v121
	v_cvt_pk_bf16_f32 v127, v122, v123
	v_cvt_pk_bf16_f32 v116, v116, v117
	v_cvt_pk_bf16_f32 v117, v118, v119
	v_cvt_pk_bf16_f32 v118, v112, v113
	v_cvt_pk_bf16_f32 v119, v114, v115
	v_permlane16_swap_b32_e32 v124, v126
	v_permlane16_swap_b32_e32 v125, v127
	global_store_dwordx4 v[168:169], v[124:127], off offset:-4096
	v_cvt_pk_bf16_f32 v108, v108, v109
	v_cvt_pk_bf16_f32 v109, v110, v111
	v_cvt_pk_bf16_f32 v110, v104, v105
	v_cvt_pk_bf16_f32 v111, v106, v107
	v_permlane16_swap_b32_e32 v116, v118
	v_permlane16_swap_b32_e32 v117, v119
	global_store_dwordx4 v[168:169], v[116:119], off
	v_cvt_pk_bf16_f32 v100, v100, v101
	v_cvt_pk_bf16_f32 v101, v102, v103
	v_cvt_pk_bf16_f32 v102, v96, v97
	v_cvt_pk_bf16_f32 v103, v98, v99
	v_permlane16_swap_b32_e32 v108, v110
	v_permlane16_swap_b32_e32 v109, v111
	global_store_dwordx4 v[170:171], v[108:111], off offset:-4096
	v_cvt_pk_bf16_f32 v92, v92, v93
	v_cvt_pk_bf16_f32 v93, v94, v95
	v_cvt_pk_bf16_f32 v94, v88, v89
	v_cvt_pk_bf16_f32 v95, v90, v91
	v_permlane16_swap_b32_e32 v100, v102
	v_permlane16_swap_b32_e32 v101, v103
	global_store_dwordx4 v[170:171], v[100:103], off
	v_cvt_pk_bf16_f32 v84, v84, v85
	v_cvt_pk_bf16_f32 v85, v86, v87
	v_cvt_pk_bf16_f32 v86, v80, v81
	v_cvt_pk_bf16_f32 v87, v82, v83
	v_permlane16_swap_b32_e32 v92, v94
	v_permlane16_swap_b32_e32 v93, v95
	global_store_dwordx4 v[172:173], v[92:95], off offset:-4096
	v_cvt_pk_bf16_f32 v76, v76, v77
	v_cvt_pk_bf16_f32 v77, v78, v79
	v_cvt_pk_bf16_f32 v78, v72, v73
	v_cvt_pk_bf16_f32 v79, v74, v75
	v_permlane16_swap_b32_e32 v84, v86
	v_permlane16_swap_b32_e32 v85, v87
	global_store_dwordx4 v[172:173], v[84:87], off
	v_cvt_pk_bf16_f32 v68, v68, v69
	v_cvt_pk_bf16_f32 v69, v70, v71
	v_cvt_pk_bf16_f32 v70, v64, v65
	v_cvt_pk_bf16_f32 v71, v66, v67
	v_permlane16_swap_b32_e32 v76, v78
	v_permlane16_swap_b32_e32 v77, v79
	global_store_dwordx4 v[174:175], v[76:79], off offset:-4096
	v_cvt_pk_bf16_f32 v60, v60, v61
	v_cvt_pk_bf16_f32 v61, v62, v63
	v_cvt_pk_bf16_f32 v62, v56, v57
	v_cvt_pk_bf16_f32 v63, v58, v59
	v_permlane16_swap_b32_e32 v68, v70
	v_permlane16_swap_b32_e32 v69, v71
	global_store_dwordx4 v[174:175], v[68:71], off
	v_cvt_pk_bf16_f32 v52, v52, v53
	v_cvt_pk_bf16_f32 v53, v54, v55
	v_cvt_pk_bf16_f32 v54, v48, v49
	v_cvt_pk_bf16_f32 v55, v50, v51
	v_permlane16_swap_b32_e32 v60, v62
	v_permlane16_swap_b32_e32 v61, v63
	global_store_dwordx4 v[176:177], v[60:63], off offset:-4096
	v_cvt_pk_bf16_f32 v44, v44, v45
	v_cvt_pk_bf16_f32 v45, v46, v47
	v_cvt_pk_bf16_f32 v46, v40, v41
	v_cvt_pk_bf16_f32 v47, v42, v43
	v_permlane16_swap_b32_e32 v52, v54
	v_permlane16_swap_b32_e32 v53, v55
	global_store_dwordx4 v[176:177], v[52:55], off
	v_cvt_pk_bf16_f32 v36, v36, v37
	v_cvt_pk_bf16_f32 v37, v38, v39
	v_cvt_pk_bf16_f32 v38, v32, v33
	v_cvt_pk_bf16_f32 v39, v34, v35
	v_permlane16_swap_b32_e32 v44, v46
	v_permlane16_swap_b32_e32 v45, v47
	global_store_dwordx4 v[178:179], v[44:47], off offset:-4096
	v_cvt_pk_bf16_f32 v28, v28, v29
	v_cvt_pk_bf16_f32 v29, v30, v31
	v_cvt_pk_bf16_f32 v30, v24, v25
	v_cvt_pk_bf16_f32 v31, v26, v27
	v_permlane16_swap_b32_e32 v36, v38
	v_permlane16_swap_b32_e32 v37, v39
	global_store_dwordx4 v[178:179], v[36:39], off
	v_cvt_pk_bf16_f32 v20, v20, v21
	v_cvt_pk_bf16_f32 v21, v22, v23
	v_cvt_pk_bf16_f32 v22, v16, v17
	v_cvt_pk_bf16_f32 v23, v18, v19
	v_permlane16_swap_b32_e32 v28, v30
	v_permlane16_swap_b32_e32 v29, v31
	global_store_dwordx4 v[180:181], v[28:31], off offset:-4096
	v_cvt_pk_bf16_f32 v12, v12, v13
	v_cvt_pk_bf16_f32 v13, v14, v15
	v_cvt_pk_bf16_f32 v14, v8, v9
	v_cvt_pk_bf16_f32 v15, v10, v11
	v_permlane16_swap_b32_e32 v20, v22
	v_permlane16_swap_b32_e32 v21, v23
	global_store_dwordx4 v[180:181], v[20:23], off
	v_cvt_pk_bf16_f32 v4, v4, v5
	v_cvt_pk_bf16_f32 v5, v6, v7
	v_cvt_pk_bf16_f32 v6, v0, v1
	v_cvt_pk_bf16_f32 v7, v2, v3
	v_permlane16_swap_b32_e32 v12, v14
	v_permlane16_swap_b32_e32 v13, v15
	global_store_dwordx4 v[182:183], v[12:15], off offset:-4096
	s_nop 1
	v_permlane16_swap_b32_e32 v4, v6
	v_permlane16_swap_b32_e32 v5, v7
	global_store_dwordx4 v[182:183], v[4:7], off
	s_mov_b32 s2, s14
	s_mov_b32 s0, s12
	s_andn2_b64 vcc, exec, s[10:11]
	s_waitcnt vmcnt(32)
	s_cbranch_vccz .LBB0_148
	s_branch .Lseam_qkvrot
